# grid barrier: top counter replicated per XCC (last arriver posts on 8 replicas, each XCC polls its own word) on top of the early write-back
# speedup vs baseline: 1.0039x; 1.0039x over previous
; __global__ void __launch_bounds__(512, 2) mega(Params p, int ph_lo, int ph_hi) {
;   extern __shared__ __attribute__((aligned(16))) char shm[];
;   cg::grid_group grid = cg::this_grid();
;   const int swave = __builtin_amdgcn_readfirstlane(threadIdx.x >> 6);
;   unsigned* bar = (unsigned*)(p.ws + OFF_BAR);
;   unsigned info = 0;
;   if (ph_hi - ph_lo > 1) {
;     if (blockIdx.x == 0) for (int i = threadIdx.x; i < 19; i += 512) __hip_atomic_store(bar + 64 * i, 0u, __ATOMIC_RELAXED, __HIP_MEMORY_SCOPE_AGENT);
_Z4mega6Paramsii:
	s_load_dwordx2 s[28:29], s[0:1], 0xf0
	s_load_dwordx4 s[8:11], s[0:1], 0xe0
	s_load_dwordx8 s[12:19], s[0:1], 0xc0
	s_add_u32 s6, s0, 0xf8
	s_load_dword s67, s[0:1], 0xf8
	s_addc_u32 s7, s1, 0
	s_mov_b32 s85, s2
	s_waitcnt lgkmcnt(0)
	v_writelane_b32 v248, s12, 0
	s_add_u32 s2, s10, 0x1ec9c000
	v_and_b32_e32 v1, 0x3ff, v0
	v_writelane_b32 v248, s13, 1
	v_writelane_b32 v248, s14, 2
	v_writelane_b32 v248, s15, 3
	v_writelane_b32 v248, s16, 4
	v_writelane_b32 v248, s17, 5
	v_writelane_b32 v248, s18, 6
	v_writelane_b32 v248, s19, 7
	v_writelane_b32 v248, s8, 8
	s_addc_u32 s3, s11, 0
	s_sub_i32 s4, s29, s28
	v_writelane_b32 v248, s9, 9
	v_readfirstlane_b32 s12, v1
	v_writelane_b32 v248, s10, 10
	s_cmp_lt_i32 s4, 2
	s_mov_b32 s4, 0
	v_writelane_b32 v248, s11, 11
	s_cbranch_scc1 .LBB0_21
	s_cmp_eq_u32 s85, 0
	s_cselect_b64 s[4:5], -1, 0
	v_cmp_gt_u32_e32 vcc, 27, v1
	s_and_b64 s[8:9], s[4:5], vcc
	s_and_saveexec_b64 s[4:5], s[8:9]
	s_cbranch_execz .LBB0_3
	v_lshlrev_b32_e32 v2, 8, v1
	v_mov_b32_e32 v3, 0
	global_store_dword v2, v3, s[2:3] sc1

; __device__ __forceinline__ void grid_barrier(unsigned* bar, unsigned k, unsigned info, int swave) {
;     ...
;       const unsigned old = __hip_atomic_fetch_add(bar + 64 * (8 + myxcc), 1u, __ATOMIC_RELAXED, __HIP_MEMORY_SCOPE_AGENT);
;       if (old + 1u == k * nmine) {
;         __builtin_amdgcn_fence(__ATOMIC_RELEASE, "agent");
;         asm volatile("s_waitcnt vmcnt(0)" ::: "memory");
;         __hip_atomic_fetch_add(bar + 64 * 16, 1u, __ATOMIC_RELAXED, __HIP_MEMORY_SCOPE_AGENT);
;       }
;       while (__hip_atomic_load(bar + 64 * 16, __ATOMIC_RELAXED, __HIP_MEMORY_SCOPE_AGENT) < k * nxcc) __builtin_amdgcn_s_sleep(1);
;       __builtin_amdgcn_fence(__ATOMIC_ACQUIRE, "agent");
;       asm volatile("s_waitcnt vmcnt(0)" ::: "memory");
.Lxb_noflush:
	v_cmp_eq_u32_e32 vcc, s2, v0
	s_and_saveexec_b64 s[2:3], vcc
	s_cbranch_execz .LBB0_33
	s_mov_b64 s[4:5], exec
	v_mbcnt_lo_u32_b32 v0, s4, 0
	buffer_wbl2 sc1
	s_waitcnt vmcnt(0)
	v_mbcnt_hi_u32_b32 v0, s5, v0
	v_cmp_eq_u32_e32 vcc, 0, v0
	s_and_b64 s[6:7], exec, vcc
	s_mov_b64 exec, s[6:7]
	s_cbranch_execz .LBB0_33
	s_bcnt1_i32_b64 s4, s[4:5]
	v_mov_b32_e32 v0, s4
	global_atomic_add v3, v0, s[86:87] offset:768
	global_atomic_add v3, v0, s[86:87] offset:1024
	global_atomic_add v3, v0, s[86:87] offset:1280
	global_atomic_add v3, v0, s[86:87] offset:1536
	global_atomic_add v3, v0, s[86:87] offset:1792
	global_atomic_add v3, v0, s[86:87] offset:2048
	global_atomic_add v3, v0, s[86:87] offset:2304
	global_atomic_add v3, v0, s[86:87] offset:2560
.LBB0_33:
	s_or_b64 exec, exec, s[2:3]
	v_readlane_b32 s4, v248, 62
	v_readlane_b32 s5, v248, 63
	s_add_u32 s4, s4, 0x1300
	s_addc_u32 s5, s5, 0
	global_load_dword v0, v3, s[4:5] sc1
	v_readlane_b32 s2, v248, 61
	v_readlane_b32 s3, v247, 43
	s_mul_i32 s2, s3, s2
	s_waitcnt vmcnt(0)
	v_cmp_le_u32_e32 vcc, s2, v0
	s_cbranch_vccnz .LBB0_35
.LBB0_34:
	s_sleep 1
	global_load_dword v0, v3, s[4:5] sc1
	s_waitcnt vmcnt(0)
	v_cmp_gt_u32_e32 vcc, s2, v0
	s_cbranch_vccnz .LBB0_34
